# aligned combo12 with the background-conversion start staggered per wave (2x48 + 8 per wave index) instead of a uniform 2x64
# baseline (speedup 1.0000x reference)
; #define LAS __attribute__((address_space(3)))
; __device__ __forceinline__ void cv_background(Frame& F, const CvPtrs& P, int s) {
;     int tv = threadIdx.x; asm volatile("" : "+v"(tv));
;     const int w = __builtin_amdgcn_readfirstlane(tv >> 6) - 1, lane = tv & 63, nbw = F.G * (NWAVES - 1);
;     LAS float* scr = (LAS float*)(F.lds + RING_OFF + (w + 1) * 16384);
;     const int sh_ = cv_bg_share(s), hi = (sh_ + 1) * CV_BG_PER < CV_BG_TOTAL ? (sh_ + 1) * CV_BG_PER : CV_BG_TOTAL;
;     for (int j = sh_ * CV_BG_PER + F.vcu * (NWAVES - 1) + w; j < hi; j += nbw) {
; __device__ __forceinline__ void xcd_barrier_cv(const XcdBarrier& b, Frame& F, const CvPtrs& P, int s, bool local) {
;     asm volatile("s_waitcnt vmcnt(0)" ::: "memory");
;     __syncthreads();
;     if (threadIdx.x < 64) { if (threadIdx.x == 0) { if (local) xcc_barrier_thread0(b); else xcd_barrier_thread0(b); } }
;     else if (cv_bg_share(s) >= 0 && cv_bg_share(s) < CV_BG_SHARES) cv_background(F, P, s);
.LBB0_769:
	s_and_b64 vcc, exec, s[0:1]
	s_cbranch_vccz .LBB0_1015
	v_readfirstlane_b32 s8, v0
	s_lshr_b32 s8, s8, 6
	s_sleep 48
	s_sleep 48
.Lbg_stag:
	s_sleep 8
	s_sub_u32 s8, s8, 1
	s_cmp_lg_u32 s8, 0
	s_cbranch_scc1 .Lbg_stag
	v_mov_b32_e32 v4, v0
	s_mov_b64 s[6:7], -1
	v_readfirstlane_b32 s8, v4
	s_mov_b64 s[0:1], 0
	s_cmp_lt_i32 s89, 5
	s_mov_b64 s[4:5], 0
	s_cbranch_scc1 .LBB0_787
	s_cmp_gt_i32 s89, 7
	s_cbranch_scc0 .LBB0_779
	s_cmp_gt_i32 s89, 8
	s_cbranch_scc0 .LBB0_776
	s_cmp_eq_u32 s89, 9
	s_mov_b64 s[4:5], -1
	s_cbranch_scc0 .LBB0_775
	s_mov_b64 s[4:5], 0
